# P7 EpiRes epilogue hand-written: 21 residual loads in flight per wave instead of 32 serialized load-wait-store steps
# speedup vs baseline: 1.0158x; 1.0032x over previous
.LBB0_978:
	s_andn2_b64 vcc, exec, s[8:9]
	s_mov_b32 s25, s34
	s_lshr_b32 s27, s25, 5
	s_mul_i32 s27, s27, 0x6000
	s_add_u32 s34, s4, s27
	s_addc_u32 s35, s5, 0
	s_add_u32 s34, s34, 0x2382000
	s_addc_u32 s35, s35, 0
	s_lshl_b32 s27, s36, 10
	s_add_u32 s34, s34, s27
	s_addc_u32 s35, s35, 0
	v_and_b32_e32 v254, 0xf, v192
	v_bfe_u32 v246, v192, 4, 2
	v_bfe_u32 v247, v192, 6, 2
	v_lshlrev_b32_e32 v247, 0x5, v247
	v_lshl_add_u32 v247, v246, 2, v247
	v_lshlrev_b32_e32 v163, 0x2, v247
	global_load_dwordx4 v[112:115], v163, s[34:35]
	global_load_dwordx4 v[116:119], v163, s[34:35] offset:64
	global_load_dwordx4 v[100:103], v163, s[34:35] offset:512
	global_load_dwordx4 v[104:107], v163, s[34:35] offset:576
	v_lshrrev_b32_e32 v246, 0x8, v192
	v_lshl_add_u32 v246, v246, 6, v254
	v_lshlrev_b32_e32 v148, 0xc, v246
	v_add_u32_e32 v148, v148, v163
	v_lshlrev_b32_e32 v162, 0xb, v246
	v_lshl_add_u32 v162, v247, 1, v162
	s_lshl_b32 s27, s25, 20
	s_add_u32 s34, s12, s27
	s_addc_u32 s35, s13, 0
	s_lshl_b32 s27, s36, 10
	s_add_u32 s34, s34, s27
	s_addc_u32 s35, s35, 0
	s_lshl_b32 s27, s25, 19
	s_add_u32 s8, s2, s27
	s_addc_u32 s9, s3, 0
	s_lshl_b32 s27, s36, 9
	s_add_u32 s8, s8, s27
	s_addc_u32 s9, s9, 0
	v_add_u32_e32 v247, 0x0, v148
	global_load_dwordx4 v[168:171], v247, s[34:35]
	global_load_dwordx4 v[172:175], v247, s[34:35] offset:64
	global_load_dwordx4 v[176:179], v247, s[34:35] offset:512
	global_load_dwordx4 v[180:183], v247, s[34:35] offset:576
	v_add_u32_e32 v246, 0x10000, v148
	global_load_dwordx4 v[184:187], v246, s[34:35]
	global_load_dwordx4 v[188:191], v246, s[34:35] offset:64
	global_load_dwordx4 v[194:197], v246, s[34:35] offset:512
	global_load_dwordx4 v[198:201], v246, s[34:35] offset:576
	v_add_u32_e32 v247, 0x20000, v148
	global_load_dwordx4 v[202:205], v247, s[34:35]
	global_load_dwordx4 v[206:209], v247, s[34:35] offset:64
	global_load_dwordx4 v[210:213], v247, s[34:35] offset:512
	global_load_dwordx4 v[214:217], v247, s[34:35] offset:576
	v_add_u32_e32 v246, 0x30000, v148
	global_load_dwordx4 v[218:221], v246, s[34:35]
	global_load_dwordx4 v[222:225], v246, s[34:35] offset:64
	global_load_dwordx4 v[226:229], v246, s[34:35] offset:512
	global_load_dwordx4 v[230:233], v246, s[34:35] offset:576
	v_add_u32_e32 v247, 0x80000, v148
	global_load_dwordx4 v[234:237], v247, s[34:35]
	global_load_dwordx4 v[238:241], v247, s[34:35] offset:64
	global_load_dwordx4 v[242:245], v247, s[34:35] offset:512
	global_load_dwordx4 v[250:253], v247, s[34:35] offset:576
	v_add_u32_e32 v246, 0x90000, v148
	global_load_dwordx4 v[158:161], v246, s[34:35]
	s_waitcnt vmcnt(20)
	v_add_u32_e32 v254, 0x0, v162
	v_pk_mul_f32 v[170:171], v[170:171], s[22:23] op_sel_hi:[1,0]
	v_pk_mul_f32 v[168:169], v[168:169], s[22:23] op_sel_hi:[1,0]
	v_pk_fma_f32 v[142:143], v[142:143], v[114:115], v[170:171]
	v_pk_fma_f32 v[140:141], v[140:141], v[112:113], v[168:169]
	s_nop 0
	global_load_dwordx4 v[168:171], v246, s[34:35] offset:64
	v_cvt_pk_bf16_f32 v140, v140, v141
	v_cvt_pk_bf16_f32 v141, v142, v143
	global_store_dwordx2 v254, v[140:141], s[8:9]
	s_waitcnt vmcnt(21)
	v_pk_mul_f32 v[174:175], v[174:175], s[22:23] op_sel_hi:[1,0]
	v_pk_mul_f32 v[172:173], v[172:173], s[22:23] op_sel_hi:[1,0]
	v_pk_fma_f32 v[138:139], v[138:139], v[118:119], v[174:175]
	v_pk_fma_f32 v[136:137], v[136:137], v[116:117], v[172:173]
	s_nop 0
	global_load_dwordx4 v[172:175], v246, s[34:35] offset:512
	v_cvt_pk_bf16_f32 v136, v136, v137
	v_cvt_pk_bf16_f32 v137, v138, v139
	global_store_dwordx2 v254, v[136:137], s[8:9] offset:32
	s_waitcnt vmcnt(22)
	v_pk_mul_f32 v[178:179], v[178:179], s[22:23] op_sel_hi:[1,0]
	v_pk_mul_f32 v[176:177], v[176:177], s[22:23] op_sel_hi:[1,0]
	v_pk_fma_f32 v[134:135], v[134:135], v[102:103], v[178:179]
	v_pk_fma_f32 v[132:133], v[132:133], v[100:101], v[176:177]
	s_nop 0
	global_load_dwordx4 v[176:179], v246, s[34:35] offset:576
	v_cvt_pk_bf16_f32 v132, v132, v133
	v_cvt_pk_bf16_f32 v133, v134, v135
	global_store_dwordx2 v254, v[132:133], s[8:9] offset:256
	s_waitcnt vmcnt(23)
	v_pk_mul_f32 v[182:183], v[182:183], s[22:23] op_sel_hi:[1,0]
	v_pk_mul_f32 v[180:181], v[180:181], s[22:23] op_sel_hi:[1,0]
	v_pk_fma_f32 v[130:131], v[130:131], v[106:107], v[182:183]
	v_pk_fma_f32 v[128:129], v[128:129], v[104:105], v[180:181]
	s_nop 0
	v_add_u32_e32 v247, 0xa0000, v148
	global_load_dwordx4 v[180:183], v247, s[34:35]
	v_cvt_pk_bf16_f32 v128, v128, v129
	v_cvt_pk_bf16_f32 v129, v130, v131
	global_store_dwordx2 v254, v[128:129], s[8:9] offset:288
	s_waitcnt vmcnt(24)
	v_add_u32_e32 v255, 0x8000, v162
	v_pk_mul_f32 v[186:187], v[186:187], s[22:23] op_sel_hi:[1,0]
	v_pk_mul_f32 v[184:185], v[184:185], s[22:23] op_sel_hi:[1,0]
	v_pk_fma_f32 v[126:127], v[126:127], v[114:115], v[186:187]
	v_pk_fma_f32 v[124:125], v[124:125], v[112:113], v[184:185]
	s_nop 0
	global_load_dwordx4 v[184:187], v247, s[34:35] offset:64
	v_cvt_pk_bf16_f32 v124, v124, v125
	v_cvt_pk_bf16_f32 v125, v126, v127
	global_store_dwordx2 v255, v[124:125], s[8:9]
	s_waitcnt vmcnt(25)
	v_pk_mul_f32 v[190:191], v[190:191], s[22:23] op_sel_hi:[1,0]
	v_pk_mul_f32 v[188:189], v[188:189], s[22:23] op_sel_hi:[1,0]
	v_pk_fma_f32 v[122:123], v[122:123], v[118:119], v[190:191]
	v_pk_fma_f32 v[120:121], v[120:121], v[116:117], v[188:189]
	s_nop 0
	global_load_dwordx4 v[188:191], v247, s[34:35] offset:512
	v_cvt_pk_bf16_f32 v120, v120, v121
	v_cvt_pk_bf16_f32 v121, v122, v123
	global_store_dwordx2 v255, v[120:121], s[8:9] offset:32
	s_waitcnt vmcnt(26)
	v_pk_mul_f32 v[196:197], v[196:197], s[22:23] op_sel_hi:[1,0]
	v_pk_mul_f32 v[194:195], v[194:195], s[22:23] op_sel_hi:[1,0]
	v_pk_fma_f32 v[110:111], v[110:111], v[102:103], v[196:197]
	v_pk_fma_f32 v[108:109], v[108:109], v[100:101], v[194:195]
	s_nop 0
	global_load_dwordx4 v[194:197], v247, s[34:35] offset:576
	v_cvt_pk_bf16_f32 v108, v108, v109
	v_cvt_pk_bf16_f32 v109, v110, v111
	global_store_dwordx2 v255, v[108:109], s[8:9] offset:256
	s_waitcnt vmcnt(27)
	v_pk_mul_f32 v[200:201], v[200:201], s[22:23] op_sel_hi:[1,0]
	v_pk_mul_f32 v[198:199], v[198:199], s[22:23] op_sel_hi:[1,0]
	v_pk_fma_f32 v[98:99], v[98:99], v[106:107], v[200:201]
	v_pk_fma_f32 v[96:97], v[96:97], v[104:105], v[198:199]
	s_nop 0
	v_add_u32_e32 v246, 0xb0000, v148
	global_load_dwordx4 v[198:201], v246, s[34:35]
	v_cvt_pk_bf16_f32 v96, v96, v97
	v_cvt_pk_bf16_f32 v97, v98, v99
	global_store_dwordx2 v255, v[96:97], s[8:9] offset:288
	s_waitcnt vmcnt(28)
	v_add_u32_e32 v254, 0x10000, v162
	v_pk_mul_f32 v[204:205], v[204:205], s[22:23] op_sel_hi:[1,0]
	v_pk_mul_f32 v[202:203], v[202:203], s[22:23] op_sel_hi:[1,0]
	v_pk_fma_f32 v[94:95], v[94:95], v[114:115], v[204:205]
	v_pk_fma_f32 v[92:93], v[92:93], v[112:113], v[202:203]
	s_nop 0
	global_load_dwordx4 v[202:205], v246, s[34:35] offset:64
	v_cvt_pk_bf16_f32 v92, v92, v93
	v_cvt_pk_bf16_f32 v93, v94, v95
	global_store_dwordx2 v254, v[92:93], s[8:9]
	s_waitcnt vmcnt(29)
	v_pk_mul_f32 v[208:209], v[208:209], s[22:23] op_sel_hi:[1,0]
	v_pk_mul_f32 v[206:207], v[206:207], s[22:23] op_sel_hi:[1,0]
	v_pk_fma_f32 v[90:91], v[90:91], v[118:119], v[208:209]
	v_pk_fma_f32 v[88:89], v[88:89], v[116:117], v[206:207]
	s_nop 0
	global_load_dwordx4 v[206:209], v246, s[34:35] offset:512
	v_cvt_pk_bf16_f32 v88, v88, v89
	v_cvt_pk_bf16_f32 v89, v90, v91
	global_store_dwordx2 v254, v[88:89], s[8:9] offset:32
	s_waitcnt vmcnt(30)
	v_pk_mul_f32 v[212:213], v[212:213], s[22:23] op_sel_hi:[1,0]
	v_pk_mul_f32 v[210:211], v[210:211], s[22:23] op_sel_hi:[1,0]
	v_pk_fma_f32 v[86:87], v[86:87], v[102:103], v[212:213]
	v_pk_fma_f32 v[84:85], v[84:85], v[100:101], v[210:211]
	s_nop 0
	global_load_dwordx4 v[210:213], v246, s[34:35] offset:576
	v_cvt_pk_bf16_f32 v84, v84, v85
	v_cvt_pk_bf16_f32 v85, v86, v87
	global_store_dwordx2 v254, v[84:85], s[8:9] offset:256
	s_waitcnt vmcnt(31)
	v_pk_mul_f32 v[216:217], v[216:217], s[22:23] op_sel_hi:[1,0]
	v_pk_mul_f32 v[214:215], v[214:215], s[22:23] op_sel_hi:[1,0]
	v_pk_fma_f32 v[82:83], v[82:83], v[106:107], v[216:217]
	v_pk_fma_f32 v[80:81], v[80:81], v[104:105], v[214:215]
	s_nop 0
	v_cvt_pk_bf16_f32 v80, v80, v81
	v_cvt_pk_bf16_f32 v81, v82, v83
	global_store_dwordx2 v254, v[80:81], s[8:9] offset:288
	s_waitcnt vmcnt(31)
	v_add_u32_e32 v255, 0x18000, v162
	v_pk_mul_f32 v[220:221], v[220:221], s[22:23] op_sel_hi:[1,0]
	v_pk_mul_f32 v[218:219], v[218:219], s[22:23] op_sel_hi:[1,0]
	v_pk_fma_f32 v[78:79], v[78:79], v[114:115], v[220:221]
	v_pk_fma_f32 v[76:77], v[76:77], v[112:113], v[218:219]
	s_nop 0
	v_cvt_pk_bf16_f32 v76, v76, v77
	v_cvt_pk_bf16_f32 v77, v78, v79
	global_store_dwordx2 v255, v[76:77], s[8:9]
	s_waitcnt vmcnt(31)
	v_pk_mul_f32 v[224:225], v[224:225], s[22:23] op_sel_hi:[1,0]
	v_pk_mul_f32 v[222:223], v[222:223], s[22:23] op_sel_hi:[1,0]
	v_pk_fma_f32 v[74:75], v[74:75], v[118:119], v[224:225]
	v_pk_fma_f32 v[72:73], v[72:73], v[116:117], v[222:223]
	s_nop 0
	v_cvt_pk_bf16_f32 v72, v72, v73
	v_cvt_pk_bf16_f32 v73, v74, v75
	global_store_dwordx2 v255, v[72:73], s[8:9] offset:32
	s_waitcnt vmcnt(31)
	v_pk_mul_f32 v[228:229], v[228:229], s[22:23] op_sel_hi:[1,0]
	v_pk_mul_f32 v[226:227], v[226:227], s[22:23] op_sel_hi:[1,0]
	v_pk_fma_f32 v[70:71], v[70:71], v[102:103], v[228:229]
	v_pk_fma_f32 v[68:69], v[68:69], v[100:101], v[226:227]
	s_nop 0
	v_cvt_pk_bf16_f32 v68, v68, v69
	v_cvt_pk_bf16_f32 v69, v70, v71
	global_store_dwordx2 v255, v[68:69], s[8:9] offset:256
	s_waitcnt vmcnt(31)
	v_pk_mul_f32 v[232:233], v[232:233], s[22:23] op_sel_hi:[1,0]
	v_pk_mul_f32 v[230:231], v[230:231], s[22:23] op_sel_hi:[1,0]
	v_pk_fma_f32 v[66:67], v[66:67], v[106:107], v[232:233]
	v_pk_fma_f32 v[64:65], v[64:65], v[104:105], v[230:231]
	s_nop 0
	v_cvt_pk_bf16_f32 v64, v64, v65
	v_cvt_pk_bf16_f32 v65, v66, v67
	global_store_dwordx2 v255, v[64:65], s[8:9] offset:288
	s_waitcnt vmcnt(31)
	v_add_u32_e32 v254, 0x40000, v162
	v_pk_mul_f32 v[236:237], v[236:237], s[22:23] op_sel_hi:[1,0]
	v_pk_mul_f32 v[234:235], v[234:235], s[22:23] op_sel_hi:[1,0]
	v_pk_fma_f32 v[62:63], v[62:63], v[114:115], v[236:237]
	v_pk_fma_f32 v[60:61], v[60:61], v[112:113], v[234:235]
	s_nop 0
	v_cvt_pk_bf16_f32 v60, v60, v61
	v_cvt_pk_bf16_f32 v61, v62, v63
	global_store_dwordx2 v254, v[60:61], s[8:9]
	s_waitcnt vmcnt(31)
	v_pk_mul_f32 v[240:241], v[240:241], s[22:23] op_sel_hi:[1,0]
	v_pk_mul_f32 v[238:239], v[238:239], s[22:23] op_sel_hi:[1,0]
	v_pk_fma_f32 v[58:59], v[58:59], v[118:119], v[240:241]
	v_pk_fma_f32 v[56:57], v[56:57], v[116:117], v[238:239]
	s_nop 0
	v_cvt_pk_bf16_f32 v56, v56, v57
	v_cvt_pk_bf16_f32 v57, v58, v59
	global_store_dwordx2 v254, v[56:57], s[8:9] offset:32
	s_waitcnt vmcnt(31)
	v_pk_mul_f32 v[244:245], v[244:245], s[22:23] op_sel_hi:[1,0]
	v_pk_mul_f32 v[242:243], v[242:243], s[22:23] op_sel_hi:[1,0]
	v_pk_fma_f32 v[54:55], v[54:55], v[102:103], v[244:245]
	v_pk_fma_f32 v[52:53], v[52:53], v[100:101], v[242:243]
	s_nop 0
	v_cvt_pk_bf16_f32 v52, v52, v53
	v_cvt_pk_bf16_f32 v53, v54, v55
	global_store_dwordx2 v254, v[52:53], s[8:9] offset:256
	s_waitcnt vmcnt(31)
	v_pk_mul_f32 v[252:253], v[252:253], s[22:23] op_sel_hi:[1,0]
	v_pk_mul_f32 v[250:251], v[250:251], s[22:23] op_sel_hi:[1,0]
	v_pk_fma_f32 v[50:51], v[50:51], v[106:107], v[252:253]
	v_pk_fma_f32 v[48:49], v[48:49], v[104:105], v[250:251]
	s_nop 0
	v_cvt_pk_bf16_f32 v48, v48, v49
	v_cvt_pk_bf16_f32 v49, v50, v51
	global_store_dwordx2 v254, v[48:49], s[8:9] offset:288
	s_waitcnt vmcnt(31)
	v_add_u32_e32 v255, 0x48000, v162
	v_pk_mul_f32 v[160:161], v[160:161], s[22:23] op_sel_hi:[1,0]
	v_pk_mul_f32 v[158:159], v[158:159], s[22:23] op_sel_hi:[1,0]
	v_pk_fma_f32 v[46:47], v[46:47], v[114:115], v[160:161]
	v_pk_fma_f32 v[44:45], v[44:45], v[112:113], v[158:159]
	s_nop 0
	v_cvt_pk_bf16_f32 v44, v44, v45
	v_cvt_pk_bf16_f32 v45, v46, v47
	global_store_dwordx2 v255, v[44:45], s[8:9]
	s_waitcnt vmcnt(31)
	v_pk_mul_f32 v[170:171], v[170:171], s[22:23] op_sel_hi:[1,0]
	v_pk_mul_f32 v[168:169], v[168:169], s[22:23] op_sel_hi:[1,0]
	v_pk_fma_f32 v[42:43], v[42:43], v[118:119], v[170:171]
	v_pk_fma_f32 v[40:41], v[40:41], v[116:117], v[168:169]
	s_nop 0
	v_cvt_pk_bf16_f32 v40, v40, v41
	v_cvt_pk_bf16_f32 v41, v42, v43
	global_store_dwordx2 v255, v[40:41], s[8:9] offset:32
	s_waitcnt vmcnt(30)
	v_pk_mul_f32 v[174:175], v[174:175], s[22:23] op_sel_hi:[1,0]
	v_pk_mul_f32 v[172:173], v[172:173], s[22:23] op_sel_hi:[1,0]
	v_pk_fma_f32 v[38:39], v[38:39], v[102:103], v[174:175]
	v_pk_fma_f32 v[36:37], v[36:37], v[100:101], v[172:173]
	s_nop 0
	v_cvt_pk_bf16_f32 v36, v36, v37
	v_cvt_pk_bf16_f32 v37, v38, v39
	global_store_dwordx2 v255, v[36:37], s[8:9] offset:256
	s_waitcnt vmcnt(29)
	v_pk_mul_f32 v[178:179], v[178:179], s[22:23] op_sel_hi:[1,0]
	v_pk_mul_f32 v[176:177], v[176:177], s[22:23] op_sel_hi:[1,0]
	v_pk_fma_f32 v[34:35], v[34:35], v[106:107], v[178:179]
	v_pk_fma_f32 v[32:33], v[32:33], v[104:105], v[176:177]
	s_nop 0
	v_cvt_pk_bf16_f32 v32, v32, v33
	v_cvt_pk_bf16_f32 v33, v34, v35
	global_store_dwordx2 v255, v[32:33], s[8:9] offset:288
	s_waitcnt vmcnt(28)
	v_add_u32_e32 v254, 0x50000, v162
	v_pk_mul_f32 v[182:183], v[182:183], s[22:23] op_sel_hi:[1,0]
	v_pk_mul_f32 v[180:181], v[180:181], s[22:23] op_sel_hi:[1,0]
	v_pk_fma_f32 v[30:31], v[30:31], v[114:115], v[182:183]
	v_pk_fma_f32 v[28:29], v[28:29], v[112:113], v[180:181]
	s_nop 0
	v_cvt_pk_bf16_f32 v28, v28, v29
	v_cvt_pk_bf16_f32 v29, v30, v31
	global_store_dwordx2 v254, v[28:29], s[8:9]
	s_waitcnt vmcnt(27)
	v_pk_mul_f32 v[186:187], v[186:187], s[22:23] op_sel_hi:[1,0]
	v_pk_mul_f32 v[184:185], v[184:185], s[22:23] op_sel_hi:[1,0]
	v_pk_fma_f32 v[26:27], v[26:27], v[118:119], v[186:187]
	v_pk_fma_f32 v[24:25], v[24:25], v[116:117], v[184:185]
	s_nop 0
	v_cvt_pk_bf16_f32 v24, v24, v25
	v_cvt_pk_bf16_f32 v25, v26, v27
	global_store_dwordx2 v254, v[24:25], s[8:9] offset:32
	s_waitcnt vmcnt(26)
	v_pk_mul_f32 v[190:191], v[190:191], s[22:23] op_sel_hi:[1,0]
	v_pk_mul_f32 v[188:189], v[188:189], s[22:23] op_sel_hi:[1,0]
	v_pk_fma_f32 v[22:23], v[22:23], v[102:103], v[190:191]
	v_pk_fma_f32 v[20:21], v[20:21], v[100:101], v[188:189]
	s_nop 0
	v_cvt_pk_bf16_f32 v20, v20, v21
	v_cvt_pk_bf16_f32 v21, v22, v23
	global_store_dwordx2 v254, v[20:21], s[8:9] offset:256
	s_waitcnt vmcnt(25)
	v_pk_mul_f32 v[196:197], v[196:197], s[22:23] op_sel_hi:[1,0]
	v_pk_mul_f32 v[194:195], v[194:195], s[22:23] op_sel_hi:[1,0]
	v_pk_fma_f32 v[18:19], v[18:19], v[106:107], v[196:197]
	v_pk_fma_f32 v[16:17], v[16:17], v[104:105], v[194:195]
	s_nop 0
	v_cvt_pk_bf16_f32 v16, v16, v17
	v_cvt_pk_bf16_f32 v17, v18, v19
	global_store_dwordx2 v254, v[16:17], s[8:9] offset:288
	s_waitcnt vmcnt(24)
	v_add_u32_e32 v255, 0x58000, v162
	v_pk_mul_f32 v[200:201], v[200:201], s[22:23] op_sel_hi:[1,0]
	v_pk_mul_f32 v[198:199], v[198:199], s[22:23] op_sel_hi:[1,0]
	v_pk_fma_f32 v[14:15], v[14:15], v[114:115], v[200:201]
	v_pk_fma_f32 v[12:13], v[12:13], v[112:113], v[198:199]
	s_nop 0
	v_cvt_pk_bf16_f32 v12, v12, v13
	v_cvt_pk_bf16_f32 v13, v14, v15
	global_store_dwordx2 v255, v[12:13], s[8:9]
	s_waitcnt vmcnt(23)
	v_pk_mul_f32 v[204:205], v[204:205], s[22:23] op_sel_hi:[1,0]
	v_pk_mul_f32 v[202:203], v[202:203], s[22:23] op_sel_hi:[1,0]
	v_pk_fma_f32 v[10:11], v[10:11], v[118:119], v[204:205]
	v_pk_fma_f32 v[8:9], v[8:9], v[116:117], v[202:203]
	s_nop 0
	v_cvt_pk_bf16_f32 v8, v8, v9
	v_cvt_pk_bf16_f32 v9, v10, v11
	global_store_dwordx2 v255, v[8:9], s[8:9] offset:32
	s_waitcnt vmcnt(22)
	v_pk_mul_f32 v[208:209], v[208:209], s[22:23] op_sel_hi:[1,0]
	v_pk_mul_f32 v[206:207], v[206:207], s[22:23] op_sel_hi:[1,0]
	v_pk_fma_f32 v[6:7], v[6:7], v[102:103], v[208:209]
	v_pk_fma_f32 v[4:5], v[4:5], v[100:101], v[206:207]
	s_nop 0
	v_cvt_pk_bf16_f32 v4, v4, v5
	v_cvt_pk_bf16_f32 v5, v6, v7
	global_store_dwordx2 v255, v[4:5], s[8:9] offset:256
	s_waitcnt vmcnt(21)
	v_pk_mul_f32 v[212:213], v[212:213], s[22:23] op_sel_hi:[1,0]
	v_pk_mul_f32 v[210:211], v[210:211], s[22:23] op_sel_hi:[1,0]
	v_pk_fma_f32 v[2:3], v[2:3], v[106:107], v[212:213]
	v_pk_fma_f32 v[0:1], v[0:1], v[104:105], v[210:211]
	s_nop 0
	v_cvt_pk_bf16_f32 v0, v0, v1
	v_cvt_pk_bf16_f32 v1, v2, v3
	global_store_dwordx2 v255, v[0:1], s[8:9] offset:288
	s_mov_b64 s[8:9], -1
	s_cbranch_vccnz .LBB0_967
	s_andn2_b64 vcc, exec, s[10:11]
	s_cbranch_vccnz .LBB0_966
	s_barrier
	s_branch .LBB0_966
